# layer-0 RMSNorm pass: first row's x loads issued before waiting for the adaLN parameter loads (both batches)
# speedup vs baseline: 1.0002x; 1.0002x over previous
; __device__ __forceinline__ void rms_phase(const float* X, const float* g, const float* mod  , bf16_t* H, int gw, int NGW, int lane) {
;     for (int b = 0; b < BATCH; ++b) {
;         f32x4 mul[4], sh[4];
; #pragma unroll
;         for (int j = 0; j < 4; ++j) { const int col = 4 * lane + 256 * j; const f32x4 gg = *(const f32x4*)(g + col), sc = *(const f32x4*)(mod + b * 3072 + 1024 + col);
;             sh[j] = *(const f32x4*)(mod + b * 3072 + col); mul[j] = gg * (sc + 1.0f); }
; #pragma unroll 4
;         for (int r = gw; r < SEQ; r += NGW) {
;             const size_t m = (size_t)b * SEQ + r;
;             const f32x4* xr = (const f32x4*)(X + m * D) + lane;
;             f32x4 v[4]; float s = 0.f;
.LBB0_96:
	s_add_u32 s8, s52, 0x1000000
	s_addc_u32 s9, s53, 0
	s_add_u32 s4, s52, 0x1400000
	s_addc_u32 s5, s53, 0
	s_add_u32 s56, s52, 0x1c00000
	s_addc_u32 s57, s53, 0
	s_cmp_lt_i32 s54, 2
	s_cselect_b64 s[0:1], -1, 0
	s_cmp_gt_i32 s55, 1
	s_cselect_b64 s[6:7], -1, 0
	s_and_b64 s[0:1], s[0:1], s[6:7]
	s_andn2_b64 vcc, exec, s[0:1]
	s_cbranch_vccnz .LBB0_128
	v_lshlrev_b32_e32 v34, 4, v154
	s_waitcnt lgkmcnt(0)
	global_load_dwordx4 v[14:17], v34, s[20:21]
	global_load_dwordx4 v[10:13], v34, s[20:21] offset:1024
	global_load_dwordx4 v[6:9], v34, s[20:21] offset:2048
	global_load_dwordx4 v[2:5], v34, s[20:21] offset:3072
	v_lshlrev_b32_e32 v1, 2, v154
	s_cmpk_lt_i32 s34, 0x2000
	v_or_b32_e32 v18, 0x100, v1
	v_or_b32_e32 v19, 0x200, v1
	v_or_b32_e32 v20, 0x300, v1
	s_cselect_b64 s[6:7], -1, 0
	s_cmpk_gt_i32 s34, 0x1fff
	v_mov_b32_e32 v35, 0
	v_lshlrev_b32_e32 v46, 2, v1
	v_lshlrev_b32_e32 v1, 2, v18
	v_lshlrev_b32_e32 v45, 2, v19
	v_lshlrev_b32_e32 v44, 2, v20
	v_lshlrev_b32_e32 v36, 3, v154
	s_cbranch_scc1 .LBB0_101
	s_add_u32 s10, s52, 0x101000
	s_addc_u32 s11, s53, 0
	global_load_dwordx4 v[54:57], v46, s[10:11]
	global_load_dwordx4 v[58:61], v1, s[10:11]
	global_load_dwordx4 v[62:65], v45, s[10:11]
	global_load_dwordx4 v[66:69], v44, s[10:11]
	global_load_dwordx4 v[18:21], v46, s[60:61]
	global_load_dwordx4 v[22:25], v1, s[60:61]
	global_load_dwordx4 v[26:29], v45, s[60:61]
	global_load_dwordx4 v[30:33], v44, s[60:61]
	v_mbcnt_lo_u32_b32 v40, -1, 0
	v_mbcnt_hi_u32_b32 v40, -1, v40
	v_and_b32_e32 v41, 64, v40
	v_xor_b32_e32 v42, 1, v40
	v_add_u32_e32 v41, 64, v41
	v_xor_b32_e32 v43, 2, v40
	v_cmp_lt_i32_e32 vcc, v42, v41
	v_xor_b32_e32 v48, 4, v40
	v_xor_b32_e32 v49, 8, v40
	v_cndmask_b32_e32 v42, v40, v42, vcc
	v_cmp_lt_i32_e32 vcc, v43, v41
	s_ashr_i32 s35, s34, 31
	v_xor_b32_e32 v50, 16, v40
	v_cndmask_b32_e32 v43, v40, v43, vcc
	v_cmp_lt_i32_e32 vcc, v48, v41
	v_xor_b32_e32 v51, 32, v40
	s_lshl_b64 s[10:11], s[34:35], 11
	v_cndmask_b32_e32 v52, v40, v48, vcc
	v_cmp_lt_i32_e32 vcc, v49, v41
	s_add_u32 s10, s52, s10
	v_mov_b32_e32 v37, v35
	v_cndmask_b32_e32 v53, v40, v49, vcc
	v_cmp_lt_i32_e32 vcc, v50, v41
	s_addc_u32 s11, s53, s11
	s_ashr_i32 s67, s66, 31
	v_cndmask_b32_e32 v70, v40, v50, vcc
	v_cmp_lt_i32_e32 vcc, v51, v41
	s_lshl_b64 s[18:19], s[34:35], 12
	s_mov_b64 s[12:13], 0xa000000
	v_cndmask_b32_e32 v40, v40, v51, vcc
	v_lshlrev_b32_e32 v51, 2, v53
	v_lshlrev_b32_e32 v53, 2, v40
	v_lshl_add_u64 v[40:41], s[10:11], 0, v[36:37]
	s_lshl_b64 s[10:11], s[66:67], 11
	s_add_u32 s18, s16, s18
	s_addc_u32 s19, s17, s19
	s_mov_b64 s[14:15], 0xc00
	v_lshlrev_b32_e32 v48, 2, v42
	v_lshlrev_b32_e32 v49, 2, v43
	v_lshl_add_u64 v[42:43], s[18:19], 0, v[34:35]
	v_lshl_add_u64 v[38:39], s[20:21], 0, v[34:35]
	v_mov_b32_e32 v47, 0x358637bd
	v_lshlrev_b32_e32 v50, 2, v52
	v_lshlrev_b32_e32 v52, 2, v70
	v_lshl_add_u64 v[40:41], v[40:41], 0, s[12:13]
	s_lshl_b64 s[12:13], s[66:67], 12
	v_lshl_add_u64 v[42:43], v[42:43], 0, s[14:15]
	global_load_dwordx4 v[176:179], v[42:43], off offset:-3072
	global_load_dwordx4 v[180:183], v[42:43], off offset:-2048
	global_load_dwordx4 v[184:187], v[42:43], off offset:-1024
	global_load_dwordx4 v[188:191], v[42:43], off
	s_mov_b32 s14, s34
	s_waitcnt vmcnt(11)
	v_pk_add_f32 v[56:57], v[56:57], 1.0 op_sel_hi:[1,0]
	v_pk_add_f32 v[54:55], v[54:55], 1.0 op_sel_hi:[1,0]
	s_waitcnt vmcnt(10)
	v_pk_add_f32 v[60:61], v[60:61], 1.0 op_sel_hi:[1,0]
	v_pk_add_f32 v[58:59], v[58:59], 1.0 op_sel_hi:[1,0]
	s_waitcnt vmcnt(9)
	v_pk_add_f32 v[64:65], v[64:65], 1.0 op_sel_hi:[1,0]
	v_pk_add_f32 v[62:63], v[62:63], 1.0 op_sel_hi:[1,0]
	s_waitcnt vmcnt(8)
	v_pk_add_f32 v[68:69], v[68:69], 1.0 op_sel_hi:[1,0]
	v_pk_add_f32 v[66:67], v[66:67], 1.0 op_sel_hi:[1,0]
	v_pk_mul_f32 v[16:17], v[16:17], v[56:57]
	v_pk_mul_f32 v[14:15], v[14:15], v[54:55]
	v_pk_mul_f32 v[12:13], v[12:13], v[60:61]
	v_pk_mul_f32 v[10:11], v[10:11], v[58:59]
	v_pk_mul_f32 v[8:9], v[8:9], v[64:65]
	v_pk_mul_f32 v[6:7], v[6:7], v[62:63]
	v_pk_mul_f32 v[4:5], v[4:5], v[68:69]
	v_pk_mul_f32 v[2:3], v[2:3], v[66:67]
	s_waitcnt vmcnt(0)
	v_mov_b32_e32 v54, v176
	v_mov_b32_e32 v55, v177
	v_mov_b32_e32 v56, v178
	v_mov_b32_e32 v57, v179
	v_mov_b32_e32 v58, v180
	v_mov_b32_e32 v59, v181
	v_mov_b32_e32 v60, v182
	v_mov_b32_e32 v61, v183
	v_mov_b32_e32 v62, v184
	v_mov_b32_e32 v63, v185
	v_mov_b32_e32 v64, v186
	v_mov_b32_e32 v65, v187
	v_mov_b32_e32 v66, v188
	v_mov_b32_e32 v67, v189
	v_mov_b32_e32 v68, v190
	v_mov_b32_e32 v69, v191
	s_branch .Lrms0_after_loads

; __device__ __forceinline__ unsigned cvt_pk_bf16(float lo, float hi) { f32x2_t v = {lo, hi}; bf16x2_t b = __builtin_convertvector(v, bf16x2_t); return __builtin_bit_cast(unsigned, b); }
; __device__ __forceinline__ void rms_phase(const float* X, const float* g, const float* mod  , bf16_t* H, int gw, int NGW, int lane) {
;     ...
;         for (int r = gw; r < SEQ; r += NGW) {
;             const size_t m = (size_t)b * SEQ + r;
;             const f32x4* xr = (const f32x4*)(X + m * D) + lane;
;             f32x4 v[4]; float s = 0.f;
; #pragma unroll
;             for (int j = 0; j < 4; ++j) { v[j] = xr[64 * j]; s += (v[j].x * v[j].x + v[j].y * v[j].y) + (v[j].z * v[j].z + v[j].w * v[j].w); }
;             const float rstd = __builtin_amdgcn_rsqf(wave_sum(s) * (1.f / D) + EPS);
;             u32x2* o8 = (u32x2*)(H + m * D) + lane;
; #pragma unroll
;             for (int j = 0; j < 4; ++j) { const f32x4 o = v[j] * rstd * mul[j] + sh[j]; u32x2 w; w.x = cvt_pk_bf16(o.x, o.y); w.y = cvt_pk_bf16(o.z, o.w); o8[64 * j] = w; }
;         }
.Lrms0_after_loads:
	s_add_i32 s14, s14, s66
	v_lshl_add_u64 v[42:43], v[42:43], 0, s[12:13]
	s_cmpk_gt_i32 s14, 0x1fff
	s_waitcnt vmcnt(3)
	v_pk_mul_f32 v[70:71], v[56:57], v[56:57]
	v_pk_mul_f32 v[72:73], v[54:55], v[54:55]
	s_waitcnt vmcnt(2)
	v_pk_mul_f32 v[74:75], v[60:61], v[60:61]
	v_pk_mul_f32 v[76:77], v[58:59], v[58:59]
	v_pk_mov_b32 v[82:83], v[72:73], v[70:71] op_sel:[1,0]
	v_mov_b32_e32 v73, v71
	v_pk_mov_b32 v[70:71], v[76:77], v[74:75] op_sel:[1,0]
	v_mov_b32_e32 v77, v75
	s_waitcnt vmcnt(1)
	v_mul_f32_e32 v78, v63, v63
	v_mul_f32_e32 v80, v65, v65
	s_waitcnt vmcnt(0)
	v_mul_f32_e32 v81, v66, v66
	v_pk_add_f32 v[72:73], v[82:83], v[72:73]
	v_pk_add_f32 v[70:71], v[70:71], v[76:77]
	v_mul_f32_e32 v35, v68, v68
	v_mul_f32_e32 v37, v69, v69
	v_mul_f32_e32 v84, v67, v67
	v_pk_fma_f32 v[74:75], v[62:63], v[62:63], v[78:79] op_sel_hi:[1,1,0]
	v_pk_fma_f32 v[78:79], v[64:65], v[64:65], v[80:81] op_sel_hi:[1,1,0]
	v_pk_add_f32 v[72:73], v[72:73], v[72:73] op_sel:[0,1] op_sel_hi:[1,0]
	v_pk_add_f32 v[70:71], v[70:71], v[70:71] op_sel:[0,1] op_sel_hi:[1,0]
	v_mov_b32_e32 v75, v35
	v_mov_b32_e32 v79, v37
	v_mov_b32_e32 v73, v81
	v_mov_b32_e32 v71, v84
	v_pk_add_f32 v[74:75], v[74:75], v[78:79]
	v_pk_add_f32 v[70:71], v[72:73], v[70:71]
	s_nop 0
	v_pk_add_f32 v[70:71], v[70:71], v[74:75]
	s_nop 0
	v_add_f32_e32 v35, v70, v71
	ds_bpermute_b32 v37, v48, v35
	s_waitcnt lgkmcnt(0)
	v_add_f32_e32 v35, v35, v37
	ds_bpermute_b32 v37, v49, v35
	s_waitcnt lgkmcnt(0)
	v_add_f32_e32 v35, v35, v37
	ds_bpermute_b32 v37, v50, v35
	s_waitcnt lgkmcnt(0)
	v_add_f32_e32 v35, v35, v37
	ds_bpermute_b32 v37, v51, v35
	s_waitcnt lgkmcnt(0)
	v_add_f32_e32 v35, v35, v37
	ds_bpermute_b32 v37, v52, v35
	s_waitcnt lgkmcnt(0)
	v_add_f32_e32 v35, v35, v37
	ds_bpermute_b32 v37, v53, v35
	s_waitcnt lgkmcnt(0)
	v_add_f32_e32 v35, v35, v37
	v_fmamk_f32 v35, v35, 0x3a800000, v47
	v_rsq_f32_e32 v70, v35
	s_nop 0
	v_pk_mul_f32 v[54:55], v[54:55], v[70:71] op_sel_hi:[1,0]
	v_pk_mul_f32 v[56:57], v[56:57], v[70:71] op_sel_hi:[1,0]
	v_pk_mul_f32 v[58:59], v[58:59], v[70:71] op_sel_hi:[1,0]
	v_pk_mul_f32 v[60:61], v[60:61], v[70:71] op_sel_hi:[1,0]
	v_pk_mul_f32 v[62:63], v[62:63], v[70:71] op_sel_hi:[1,0]
	v_pk_mul_f32 v[64:65], v[64:65], v[70:71] op_sel_hi:[1,0]
	v_pk_mul_f32 v[66:67], v[66:67], v[70:71] op_sel_hi:[1,0]
	v_pk_mul_f32 v[68:69], v[68:69], v[70:71] op_sel_hi:[1,0]
	v_pk_fma_f32 v[56:57], v[16:17], v[56:57], v[20:21]
	v_pk_fma_f32 v[54:55], v[14:15], v[54:55], v[18:19]
	v_pk_fma_f32 v[60:61], v[12:13], v[60:61], v[24:25]
	v_pk_fma_f32 v[58:59], v[10:11], v[58:59], v[22:23]
	v_pk_fma_f32 v[64:65], v[8:9], v[64:65], v[28:29]
	v_pk_fma_f32 v[62:63], v[6:7], v[62:63], v[26:27]
	v_pk_fma_f32 v[68:69], v[4:5], v[68:69], v[32:33]
	v_pk_fma_f32 v[66:67], v[2:3], v[66:67], v[30:31]
	v_cvt_pk_bf16_f32 v54, v54, v55
	v_cvt_pk_bf16_f32 v55, v56, v57
	v_cvt_pk_bf16_f32 v56, v58, v59
	v_cvt_pk_bf16_f32 v57, v60, v61
	v_cvt_pk_bf16_f32 v58, v62, v63
	v_cvt_pk_bf16_f32 v59, v64, v65
	v_cvt_pk_bf16_f32 v60, v66, v67
	v_cvt_pk_bf16_f32 v61, v68, v69
	global_store_dwordx2 v[40:41], v[54:55], off
	global_store_dwordx2 v[40:41], v[56:57], off offset:512
	global_store_dwordx2 v[40:41], v[58:59], off offset:1024
	global_store_dwordx2 v[40:41], v[60:61], off offset:1536
	v_lshl_add_u64 v[40:41], v[40:41], 0, s[10:11]
	s_cbranch_scc0 .LBB0_99
	global_load_dwordx4 v[14:17], v[38:39], off
	global_load_dwordx4 v[10:13], v[38:39], off offset:1024
	global_load_dwordx4 v[6:9], v[38:39], off offset:2048
	global_load_dwordx4 v[2:5], v[38:39], off offset:3072
; __device__ __forceinline__ void rms_phase(const float* X, const float* g, const float* mod  , bf16_t* H, int gw, int NGW, int lane) {
;     for (int b = 0; b < BATCH; ++b) {
;         f32x4 mul[4], sh[4];
; #pragma unroll
;         for (int j = 0; j < 4; ++j) { const int col = 4 * lane + 256 * j; const f32x4 gg = *(const f32x4*)(g + col), sc = *(const f32x4*)(mod + b * 3072 + 1024 + col);
;             sh[j] = *(const f32x4*)(mod + b * 3072 + col); mul[j] = gg * (sc + 1.0f); }
; #pragma unroll 4
;         for (int r = gw; r < SEQ; r += NGW) {
;             const size_t m = (size_t)b * SEQ + r;
;             const f32x4* xr = (const f32x4*)(X + m * D) + lane;
;             f32x4 v[4]; float s = 0.f;
.LBB0_101:
	s_andn2_b64 vcc, exec, s[6:7]
	s_cbranch_vccnz .LBB0_104
	s_add_u32 s6, s52, 0x103000
	s_addc_u32 s7, s53, 0
	s_add_u32 s10, s52, 0x104000
	s_addc_u32 s11, s53, 0
	global_load_dwordx4 v[48:51], v46, s[10:11]
	global_load_dwordx4 v[52:55], v1, s[10:11]
	global_load_dwordx4 v[56:59], v45, s[10:11]
	global_load_dwordx4 v[60:63], v44, s[10:11]
	global_load_dwordx4 v[18:21], v46, s[6:7]
	global_load_dwordx4 v[22:25], v1, s[6:7]
	global_load_dwordx4 v[26:29], v45, s[6:7]
	global_load_dwordx4 v[30:33], v44, s[6:7]
	v_mbcnt_lo_u32_b32 v37, -1, 0
	v_mbcnt_hi_u32_b32 v38, -1, v37
	v_and_b32_e32 v39, 64, v38
	v_xor_b32_e32 v40, 1, v38
	v_add_u32_e32 v39, 64, v39
	v_xor_b32_e32 v41, 2, v38
	s_ashr_i32 s35, s34, 31
	v_cmp_lt_i32_e32 vcc, v40, v39
	v_xor_b32_e32 v42, 4, v38
	s_lshl_b64 s[6:7], s[34:35], 12
	v_cndmask_b32_e32 v40, v38, v40, vcc
	v_cmp_lt_i32_e32 vcc, v41, v39
	v_xor_b32_e32 v43, 8, v38
	s_add_u32 s6, s16, s6
	v_cndmask_b32_e32 v41, v38, v41, vcc
	v_cmp_lt_i32_e32 vcc, v42, v39
	v_mov_b32_e32 v35, 0
	v_xor_b32_e32 v44, 16, v38
	v_cndmask_b32_e32 v42, v38, v42, vcc
	v_cmp_lt_i32_e32 vcc, v43, v39
	s_addc_u32 s7, s17, s7
	s_ashr_i32 s67, s66, 31
	v_mov_b32_e32 v37, v35
	v_xor_b32_e32 v45, 32, v38
	v_cndmask_b32_e32 v43, v38, v43, vcc
	v_cmp_lt_i32_e32 vcc, v44, v39
	s_lshl_b64 s[14:15], s[34:35], 11
	v_lshl_add_u64 v[34:35], s[6:7], 0, v[34:35]
	s_lshl_b64 s[6:7], s[66:67], 12
	v_cndmask_b32_e32 v44, v38, v44, vcc
	v_cmp_lt_i32_e32 vcc, v45, v39
	s_add_u32 s14, s52, s14
	s_addc_u32 s15, s53, s15
	v_cndmask_b32_e32 v45, v38, v45, vcc
	s_mov_b64 s[10:11], 0x2000000
	s_mov_b64 s[12:13], 0xb000000
	v_lshlrev_b32_e32 v38, 2, v40
	v_lshlrev_b32_e32 v39, 2, v41
	v_lshlrev_b32_e32 v40, 2, v42
	v_lshlrev_b32_e32 v41, 2, v43
	v_lshlrev_b32_e32 v42, 2, v44
	v_lshlrev_b32_e32 v43, 2, v45
	v_lshl_add_u64 v[36:37], s[14:15], 0, v[36:37]
	v_mov_b32_e32 v1, 0x358637bd
	v_lshl_add_u64 v[34:35], v[34:35], 0, s[10:11]
	global_load_dwordx4 v[176:179], v[34:35], off
	global_load_dwordx4 v[180:183], v[34:35], off offset:1024
	global_load_dwordx4 v[184:187], v[34:35], off offset:2048
	global_load_dwordx4 v[188:191], v[34:35], off offset:3072
	s_lshl_b64 s[10:11], s[66:67], 11
	v_lshl_add_u64 v[36:37], v[36:37], 0, s[12:13]
	s_mov_b32 s12, s34
	s_waitcnt vmcnt(11)
	v_pk_add_f32 v[44:45], v[50:51], 1.0 op_sel_hi:[1,0]
	v_pk_add_f32 v[46:47], v[48:49], 1.0 op_sel_hi:[1,0]
	s_waitcnt vmcnt(10)
	v_pk_add_f32 v[48:49], v[54:55], 1.0 op_sel_hi:[1,0]
	v_pk_add_f32 v[50:51], v[52:53], 1.0 op_sel_hi:[1,0]
	s_waitcnt vmcnt(9)
	v_pk_add_f32 v[52:53], v[58:59], 1.0 op_sel_hi:[1,0]
	v_pk_add_f32 v[54:55], v[56:57], 1.0 op_sel_hi:[1,0]
	s_waitcnt vmcnt(8)
	v_pk_add_f32 v[56:57], v[62:63], 1.0 op_sel_hi:[1,0]
	v_pk_add_f32 v[58:59], v[60:61], 1.0 op_sel_hi:[1,0]
	v_pk_mul_f32 v[16:17], v[16:17], v[44:45]
	v_pk_mul_f32 v[14:15], v[14:15], v[46:47]
	v_pk_mul_f32 v[12:13], v[12:13], v[48:49]
	v_pk_mul_f32 v[10:11], v[10:11], v[50:51]
	v_pk_mul_f32 v[8:9], v[8:9], v[52:53]
	v_pk_mul_f32 v[6:7], v[6:7], v[54:55]
	v_pk_mul_f32 v[4:5], v[4:5], v[56:57]
	v_pk_mul_f32 v[2:3], v[2:3], v[58:59]
	s_waitcnt vmcnt(0)
	v_mov_b32_e32 v44, v176
	v_mov_b32_e32 v45, v177
	v_mov_b32_e32 v46, v178
	v_mov_b32_e32 v47, v179
	v_mov_b32_e32 v48, v180
	v_mov_b32_e32 v49, v181
	v_mov_b32_e32 v50, v182
	v_mov_b32_e32 v51, v183
	v_mov_b32_e32 v52, v184
	v_mov_b32_e32 v53, v185
	v_mov_b32_e32 v54, v186
	v_mov_b32_e32 v55, v187
	v_mov_b32_e32 v56, v188
	v_mov_b32_e32 v57, v189
	v_mov_b32_e32 v58, v190
	v_mov_b32_e32 v59, v191
	s_branch .Lrms1_after_loads

; __device__ __forceinline__ unsigned cvt_pk_bf16(float lo, float hi) { f32x2_t v = {lo, hi}; bf16x2_t b = __builtin_convertvector(v, bf16x2_t); return __builtin_bit_cast(unsigned, b); }
; __device__ __forceinline__ void rms_phase(const float* X, const float* g, const float* mod  , bf16_t* H, int gw, int NGW, int lane) {
;     ...
;         for (int r = gw; r < SEQ; r += NGW) {
;             const size_t m = (size_t)b * SEQ + r;
;             const f32x4* xr = (const f32x4*)(X + m * D) + lane;
;             f32x4 v[4]; float s = 0.f;
; #pragma unroll
;             for (int j = 0; j < 4; ++j) { v[j] = xr[64 * j]; s += (v[j].x * v[j].x + v[j].y * v[j].y) + (v[j].z * v[j].z + v[j].w * v[j].w); }
;             const float rstd = __builtin_amdgcn_rsqf(wave_sum(s) * (1.f / D) + EPS);
;             u32x2* o8 = (u32x2*)(H + m * D) + lane;
; #pragma unroll
;             for (int j = 0; j < 4; ++j) { const f32x4 o = v[j] * rstd * mul[j] + sh[j]; u32x2 w; w.x = cvt_pk_bf16(o.x, o.y); w.y = cvt_pk_bf16(o.z, o.w); o8[64 * j] = w; }
;         }
.Lrms1_after_loads:
	s_add_i32 s12, s12, s66
	v_lshl_add_u64 v[34:35], v[34:35], 0, s[6:7]
	s_cmpk_gt_i32 s12, 0x1fff
	s_waitcnt vmcnt(3)
	v_pk_mul_f32 v[60:61], v[46:47], v[46:47]
	v_pk_mul_f32 v[62:63], v[44:45], v[44:45]
	s_waitcnt vmcnt(2)
	v_pk_mul_f32 v[64:65], v[50:51], v[50:51]
	v_pk_mul_f32 v[66:67], v[48:49], v[48:49]
	v_pk_mov_b32 v[72:73], v[62:63], v[60:61] op_sel:[1,0]
	v_mov_b32_e32 v63, v61
	v_pk_mov_b32 v[60:61], v[66:67], v[64:65] op_sel:[1,0]
	v_mov_b32_e32 v67, v65
	s_waitcnt vmcnt(0)
	v_mul_f32_e32 v71, v58, v58
	v_mul_f32_e32 v68, v53, v53
	v_mul_f32_e32 v70, v55, v55
	v_pk_add_f32 v[62:63], v[72:73], v[62:63]
	v_pk_add_f32 v[60:61], v[60:61], v[66:67]
	v_mul_f32_e32 v74, v59, v59
	v_mul_f32_e32 v75, v56, v56
	v_mul_f32_e32 v76, v57, v57
	v_pk_fma_f32 v[64:65], v[52:53], v[52:53], v[68:69] op_sel_hi:[1,1,0]
	v_pk_fma_f32 v[68:69], v[54:55], v[54:55], v[70:71] op_sel_hi:[1,1,0]
	v_pk_add_f32 v[62:63], v[62:63], v[62:63] op_sel:[0,1] op_sel_hi:[1,0]
	v_pk_add_f32 v[60:61], v[60:61], v[60:61] op_sel:[0,1] op_sel_hi:[1,0]
	v_mov_b32_e32 v65, v71
	v_mov_b32_e32 v69, v74
	v_mov_b32_e32 v63, v75
	v_mov_b32_e32 v61, v76
	v_pk_add_f32 v[64:65], v[64:65], v[68:69]
	v_pk_add_f32 v[60:61], v[62:63], v[60:61]
	s_nop 0
	v_pk_add_f32 v[60:61], v[60:61], v[64:65]
	s_nop 0
	v_add_f32_e32 v60, v60, v61
	ds_bpermute_b32 v61, v38, v60
	s_waitcnt lgkmcnt(0)
	v_add_f32_e32 v60, v60, v61
	ds_bpermute_b32 v61, v39, v60
	s_waitcnt lgkmcnt(0)
	v_add_f32_e32 v60, v60, v61
	ds_bpermute_b32 v61, v40, v60
	s_waitcnt lgkmcnt(0)
	v_add_f32_e32 v60, v60, v61
	ds_bpermute_b32 v61, v41, v60
	s_waitcnt lgkmcnt(0)
	v_add_f32_e32 v60, v60, v61
	ds_bpermute_b32 v61, v42, v60
	s_waitcnt lgkmcnt(0)
	v_add_f32_e32 v60, v60, v61
	ds_bpermute_b32 v61, v43, v60
	s_waitcnt lgkmcnt(0)
	v_add_f32_e32 v60, v60, v61
	v_fmamk_f32 v60, v60, 0x3a800000, v1
	v_rsq_f32_e32 v60, v60
	s_nop 0
	v_pk_mul_f32 v[44:45], v[44:45], v[60:61] op_sel_hi:[1,0]
	v_pk_mul_f32 v[46:47], v[46:47], v[60:61] op_sel_hi:[1,0]
	v_pk_mul_f32 v[48:49], v[48:49], v[60:61] op_sel_hi:[1,0]
	v_pk_mul_f32 v[50:51], v[50:51], v[60:61] op_sel_hi:[1,0]
	v_pk_mul_f32 v[52:53], v[52:53], v[60:61] op_sel_hi:[1,0]
	v_pk_mul_f32 v[54:55], v[54:55], v[60:61] op_sel_hi:[1,0]
	v_pk_mul_f32 v[56:57], v[56:57], v[60:61] op_sel_hi:[1,0]
	v_pk_mul_f32 v[58:59], v[58:59], v[60:61] op_sel_hi:[1,0]
	v_pk_fma_f32 v[46:47], v[16:17], v[46:47], v[20:21]
	v_pk_fma_f32 v[44:45], v[14:15], v[44:45], v[18:19]
	v_pk_fma_f32 v[50:51], v[12:13], v[50:51], v[24:25]
	v_pk_fma_f32 v[48:49], v[10:11], v[48:49], v[22:23]
	v_pk_fma_f32 v[54:55], v[8:9], v[54:55], v[28:29]
	v_pk_fma_f32 v[52:53], v[6:7], v[52:53], v[26:27]
	v_pk_fma_f32 v[58:59], v[4:5], v[58:59], v[32:33]
	v_pk_fma_f32 v[56:57], v[2:3], v[56:57], v[30:31]
	v_cvt_pk_bf16_f32 v44, v44, v45
	v_cvt_pk_bf16_f32 v45, v46, v47
	v_cvt_pk_bf16_f32 v46, v48, v49
	v_cvt_pk_bf16_f32 v47, v50, v51
	v_cvt_pk_bf16_f32 v48, v52, v53
	v_cvt_pk_bf16_f32 v49, v54, v55
	v_cvt_pk_bf16_f32 v50, v56, v57
	v_cvt_pk_bf16_f32 v51, v58, v59
	global_store_dwordx2 v[36:37], v[44:45], off
	global_store_dwordx2 v[36:37], v[46:47], off offset:512
	global_store_dwordx2 v[36:37], v[48:49], off offset:1024
	global_store_dwordx2 v[36:37], v[50:51], off offset:1536
	v_lshl_add_u64 v[36:37], v[36:37], 0, s[10:11]
	s_cbranch_scc0 .LBB0_103
